# prep: CKV buffer fill as a few 16-byte stores / one float4 conversion per thread instead of a 28-trip per-element loop
# speedup vs baseline: 1.0054x; 1.0054x over previous
.LBB0_1063:
	s_or_b64 exec, exec, s[4:5]
	s_mov_b64 s[4:5], 0x380000
	v_cmp_gt_u64_e32 vcc, s[4:5], v[4:5]
	s_and_saveexec_b64 s[4:5], vcc
	s_cbranch_execz .LBB0_1072
	s_add_u32 s10, s80, 0x10d18000
	s_addc_u32 s11, s81, 0
	s_load_dwordx2 s[12:13], s[8:9], 0x30
	v_mov_b32_e32 v10, 0
	v_mov_b32_e32 v11, 0
	v_mov_b32_e32 v12, 0
	v_mov_b32_e32 v13, 0
	v_lshrrev_b32_e32 v7, 4, v4
	v_and_b32_e32 v8, 15, v4
	v_lshlrev_b32_e32 v7, 9, v7
	v_lshl_add_u32 v7, v8, 4, v7
	global_store_dwordx4 v7, v[10:13], s[10:11] offset:256
	v_cmp_gt_u32_e32 vcc, 0x18000, v4
	s_and_saveexec_b64 s[14:15], vcc
	v_add_u32_e32 v7, 0x400000, v7
	s_nop 0
	global_store_dwordx4 v7, v[10:13], s[10:11] offset:256
	s_or_b64 exec, exec, s[14:15]
	v_cmp_gt_u32_e32 vcc, 0x10000, v4
	s_and_saveexec_b64 s[14:15], vcc
	s_cbranch_execz .Lckv_done
	v_lshrrev_b32_e32 v6, 15, v4
	v_bfe_u32 v7, v4, 5, 10
	v_and_b32_e32 v8, 31, v4
	v_lshrrev_b32_e32 v9, 9, v7
	v_and_b32_e32 v14, 0x1ff, v7
	v_lshl_add_u32 v9, v9, 1, v6
	v_lshl_add_u32 v9, v9, 9, v14
	v_lshlrev_b32_e32 v9, 9, v9
	v_lshl_or_b32 v9, v8, 4, v9
	s_waitcnt lgkmcnt(0)
	global_load_dwordx4 v[14:17], v9, s[12:13]
	v_mul_u32_u24_e32 v6, 0x1c00, v6
	v_add_u32_e32 v6, v6, v7
	v_add_u32_e32 v6, 0x1800, v6
	v_lshlrev_b32_e32 v6, 9, v6
	v_lshl_or_b32 v6, v8, 3, v6
	s_waitcnt vmcnt(0)
	v_cvt_pk_bf16_f32 v14, v14, v15
	v_cvt_pk_bf16_f32 v15, v16, v17
	global_store_dwordx2 v6, v[14:15], s[10:11]
.Lckv_done:
	s_or_b64 exec, exec, s[14:15]
.LBB0_1072:
	s_or_b64 exec, exec, s[4:5]
	s_mov_b64 s[4:5], 0x20000
	v_cmp_gt_u64_e32 vcc, s[4:5], v[4:5]
	v_and_b32_e32 v34, 63, v2
	s_and_saveexec_b64 s[4:5], vcc
	s_cbranch_execz .LBB0_1075
	s_ashr_i32 s1, s0, 31
	s_lshl_b64 s[0:1], s[0:1], 9
	s_mov_b64 s[6:7], 0
